# P0 weight transposes: the read-once f32 weight loads are non-temporal (nt)
# speedup vs baseline: 1.0237x; 1.0237x over previous
.LBB0_23:
	s_mul_hi_i32 s30, s90, 0xcb8727c1
	s_add_i32 s30, s30, s90
	s_lshr_b32 s34, s30, 31
	s_ashr_i32 s30, s30, 12
	s_add_i32 s34, s30, s34
	s_mul_i32 s30, s34, 0xffffebe0
	s_add_i32 s91, s90, s30
	s_cmpk_gt_i32 s91, 0x8ff
	s_mov_b64 s[36:37], -1
	s_cbranch_scc0 .LBB0_37
	s_cmpk_gt_u32 s91, 0xeff
	s_cbranch_scc0 .LBB0_34
	s_cmpk_gt_u32 s91, 0x11ff
	s_cbranch_scc0 .LBB0_31
	s_cmpk_gt_u32 s91, 0x13ff
	s_cbranch_scc0 .LBB0_28
	s_add_i32 s30, s91, 0xffffec00
	s_lshr_b32 s30, s30, 3
	s_ashr_i32 s35, s34, 31
	s_lshl_b64 s[36:37], s[30:31], 14
	s_lshl_b64 s[92:93], s[34:35], 16
	s_add_u32 s36, s36, s92
	s_addc_u32 s37, s37, s93
	s_lshl_b64 s[92:93], s[36:37], 2
	s_waitcnt lgkmcnt(0)
	s_add_u32 s35, s26, s92
	s_addc_u32 s92, s27, s93
	s_lshl_b64 s[36:37], s[36:37], 1
	s_add_u32 s93, s41, s36
	s_addc_u32 s94, s42, s37
	s_and_b32 s30, s91, 7
	s_add_i32 s36, s30, 0xfffc
	s_and_b32 s36, s36, 0xffff
	s_min_u32 s36, s30, s36
	s_cmp_gt_u32 s30, 3
	s_cselect_b32 s95, 64, 0
	s_lshl_b32 s30, s36, 5
	s_lshl_b32 s36, s36, 7
	s_add_u32 s36, s35, s36
	v_or_b32_e32 v5, s95, v6
	s_addc_u32 s37, s92, 0
	v_lshl_add_u64 v[20:21], s[36:37], 0, v[2:3]
	v_lshlrev_b32_e32 v22, 9, v5
	v_mov_b32_e32 v23, v3
	v_lshl_add_u64 v[20:21], v[20:21], 0, v[22:23]
	s_movk_i32 s35, 0x1000
	v_add_co_u32_e32 v22, vcc, s35, v20
	s_movk_i32 s35, 0x3000
	s_nop 0
	v_addc_co_u32_e32 v23, vcc, 0, v21, vcc
	v_add_co_u32_e32 v24, vcc, s47, v20
	s_nop 1
	v_addc_co_u32_e32 v25, vcc, 0, v21, vcc
	v_add_co_u32_e32 v26, vcc, s35, v20
	s_movk_i32 s35, 0x5000
	s_nop 0
	v_addc_co_u32_e32 v27, vcc, 0, v21, vcc
	v_add_co_u32_e32 v28, vcc, s48, v20
	s_nop 1
	v_addc_co_u32_e32 v29, vcc, 0, v21, vcc
	global_load_dword v5, v[20:21], off nt
	global_load_dword v30, v[20:21], off offset:1024 nt
	global_load_dword v31, v[20:21], off offset:2048 nt
	global_load_dword v32, v[20:21], off offset:3072 nt
	global_load_dword v33, v[22:23], off offset:1024 nt
	global_load_dword v34, v[22:23], off offset:2048 nt
	global_load_dword v35, v[22:23], off offset:3072 nt
	global_load_dword v36, v[26:27], off offset:1024 nt
	global_load_dword v37, v[26:27], off offset:2048 nt
	s_nop 0
	global_load_dword v26, v[26:27], off offset:3072 nt
	s_nop 0
	global_load_dword v27, v[24:25], off offset:-4096 nt
	global_load_dword v38, v[24:25], off nt
	global_load_dword v39, v[24:25], off offset:1024 nt
	global_load_dword v40, v[24:25], off offset:2048 nt
	global_load_dword v41, v[24:25], off offset:3072 nt
	global_load_dword v42, v[28:29], off offset:-4096 nt
	global_load_dword v43, v[28:29], off nt
	v_add_co_u32_e32 v22, vcc, s35, v20
	s_movk_i32 s35, 0x7000
	s_nop 0
	v_addc_co_u32_e32 v23, vcc, 0, v21, vcc
	v_add_co_u32_e32 v24, vcc, s49, v20
	s_nop 1
	v_addc_co_u32_e32 v25, vcc, 0, v21, vcc
	v_add_co_u32_e32 v20, vcc, s35, v20
	global_load_dword v44, v[28:29], off offset:1024 nt
	global_load_dword v45, v[28:29], off offset:2048 nt
	s_nop 0
	global_load_dword v28, v[28:29], off offset:3072 nt
	s_nop 0
	global_load_dword v29, v[24:25], off offset:-4096 nt
	global_load_dword v46, v[24:25], off nt
	global_load_dword v47, v[24:25], off offset:1024 nt
	global_load_dword v48, v[24:25], off offset:2048 nt
	s_nop 0
	global_load_dword v24, v[24:25], off offset:3072 nt
	v_addc_co_u32_e32 v21, vcc, 0, v21, vcc
	global_load_dword v25, v[22:23], off offset:1024 nt
	global_load_dword v49, v[22:23], off offset:2048 nt
	s_nop 0
	global_load_dword v22, v[22:23], off offset:3072 nt
	s_nop 0
	global_load_dword v23, v[20:21], off nt
	global_load_dword v50, v[20:21], off offset:1024 nt
	global_load_dword v51, v[20:21], off offset:2048 nt
	s_nop 0
	global_load_dword v20, v[20:21], off offset:3072 nt
	s_lshl_b32 s35, s95, 1
	s_add_u32 s36, s93, s35
	s_addc_u32 s37, s94, 0
	s_waitcnt vmcnt(30)
	ds_write2_b32 v7, v5, v30 offset1:66
	s_waitcnt vmcnt(28)
	ds_write2_b32 v7, v31, v32 offset0:132 offset1:198
	s_waitcnt vmcnt(21)
	ds_write2_b32 v13, v27, v33 offset0:8 offset1:74
	ds_write2_b32 v13, v34, v35 offset0:140 offset1:206
	s_waitcnt vmcnt(19)
	ds_write2_b32 v14, v38, v39 offset0:16 offset1:82
	s_waitcnt vmcnt(17)
	ds_write2_b32 v14, v40, v41 offset0:148 offset1:214
	s_waitcnt vmcnt(16)
	ds_write2_b32 v15, v42, v36 offset0:24 offset1:90
	ds_write2_b32 v15, v37, v26 offset0:156 offset1:222
	s_waitcnt vmcnt(14)
	ds_write2_b32 v16, v43, v44 offset0:32 offset1:98
	s_waitcnt vmcnt(12)
	ds_write2_b32 v16, v45, v28 offset0:164 offset1:230
	s_waitcnt vmcnt(6)
	ds_write2_b32 v17, v29, v25 offset0:40 offset1:106
	s_waitcnt vmcnt(4)
	ds_write2_b32 v17, v49, v22 offset0:172 offset1:238
	ds_write2_b32 v18, v46, v47 offset0:48 offset1:114
	ds_write2_b32 v18, v48, v24 offset0:180 offset1:246
	s_waitcnt vmcnt(2)
	ds_write2_b32 v19, v23, v50 offset0:56 offset1:122
	s_waitcnt vmcnt(0)
	ds_write2_b32 v19, v51, v20 offset0:188 offset1:254
	s_waitcnt lgkmcnt(0)
	ds_read2_b32 v[24:25], v9 offset1:8
	ds_read2_b32 v[28:29], v9 offset0:33 offset1:41
	ds_read2_b32 v[30:31], v9 offset0:66 offset1:74
	v_mov_b32_e32 v5, v3
	ds_read2_b32 v[32:33], v9 offset0:99 offset1:107
	v_lshl_add_u64 v[26:27], s[36:37], 0, v[4:5]
	s_waitcnt lgkmcnt(3)
	v_bfe_u32 v5, v24, 16, 1
	v_add3_u32 v5, v24, v5, s51
	s_waitcnt lgkmcnt(2)
	v_bfe_u32 v20, v28, 16, 1
	ds_read2_b32 v[34:35], v9 offset0:132 offset1:140
	v_lshrrev_b32_e32 v5, 16, v5
	v_add3_u32 v20, v28, v20, s51
	ds_read2_b32 v[36:37], v9 offset0:165 offset1:173
	v_and_or_b32 v20, v20, s52, v5
	s_waitcnt lgkmcnt(3)
	v_bfe_u32 v5, v30, 16, 1
	v_add3_u32 v5, v30, v5, s51
	s_waitcnt lgkmcnt(2)
	v_bfe_u32 v21, v32, 16, 1
	ds_read2_b32 v[38:39], v9 offset0:198 offset1:206
	v_lshrrev_b32_e32 v5, 16, v5
	v_add3_u32 v21, v32, v21, s51
	ds_read2_b32 v[40:41], v9 offset0:231 offset1:239
	v_and_or_b32 v21, v21, s52, v5
	s_waitcnt lgkmcnt(3)
	v_bfe_u32 v5, v34, 16, 1
	v_add3_u32 v5, v34, v5, s51
	s_waitcnt lgkmcnt(2)
	v_bfe_u32 v22, v36, 16, 1
	v_lshrrev_b32_e32 v5, 16, v5
	v_add3_u32 v22, v36, v22, s51
	v_and_or_b32 v22, v22, s52, v5
	s_waitcnt lgkmcnt(1)
	v_bfe_u32 v5, v38, 16, 1
	v_add3_u32 v5, v38, v5, s51
	s_waitcnt lgkmcnt(0)
	v_bfe_u32 v23, v40, 16, 1
	v_lshrrev_b32_e32 v5, 16, v5
	v_add3_u32 v23, v40, v23, s51
	v_and_or_b32 v23, v23, s52, v5
	v_or_b32_e32 v5, s30, v8
	v_lshlrev_b32_e32 v42, 8, v5
	v_mov_b32_e32 v43, v3
	v_lshl_add_u64 v[42:43], v[26:27], 0, v[42:43]
	v_bfe_u32 v5, v25, 16, 1
	global_store_dwordx4 v[42:43], v[20:23], off sc1
	v_add3_u32 v5, v25, v5, s51
	v_lshrrev_b32_e32 v5, 16, v5
	v_bfe_u32 v20, v29, 16, 1
	v_add3_u32 v20, v29, v20, s51
	v_and_or_b32 v20, v20, s52, v5
	v_bfe_u32 v5, v31, 16, 1
	v_add3_u32 v5, v31, v5, s51
	v_bfe_u32 v21, v33, 16, 1
	v_lshrrev_b32_e32 v5, 16, v5
	v_add3_u32 v21, v33, v21, s51
	v_and_or_b32 v21, v21, s52, v5
	v_bfe_u32 v5, v35, 16, 1
	v_add3_u32 v5, v35, v5, s51
	v_bfe_u32 v22, v37, 16, 1
	v_lshrrev_b32_e32 v5, 16, v5
	v_add3_u32 v22, v37, v22, s51
	v_and_or_b32 v22, v22, s52, v5
	v_bfe_u32 v5, v39, 16, 1
	v_add3_u32 v5, v39, v5, s51
	v_bfe_u32 v23, v41, 16, 1
	v_lshrrev_b32_e32 v5, 16, v5
	v_add3_u32 v23, v41, v23, s51
	v_and_or_b32 v23, v23, s52, v5
	v_or_b32_e32 v5, s30, v10
	v_lshlrev_b32_e32 v24, 8, v5
	v_mov_b32_e32 v25, v3
	ds_read2_b32 v[28:29], v9 offset0:16 offset1:24
	v_lshl_add_u64 v[24:25], v[26:27], 0, v[24:25]
	global_store_dwordx4 v[24:25], v[20:23], off sc1
	ds_read2_b32 v[24:25], v9 offset0:49 offset1:57
	ds_read2_b32 v[30:31], v9 offset0:82 offset1:90
	ds_read2_b32 v[32:33], v9 offset0:115 offset1:123
	s_waitcnt lgkmcnt(3)
	v_bfe_u32 v5, v28, 16, 1
	v_add3_u32 v5, v28, v5, s51
	s_waitcnt lgkmcnt(2)
	v_bfe_u32 v20, v24, 16, 1
	ds_read2_b32 v[34:35], v9 offset0:148 offset1:156
	v_lshrrev_b32_e32 v5, 16, v5
	v_add3_u32 v20, v24, v20, s51
	ds_read2_b32 v[36:37], v9 offset0:181 offset1:189
	v_and_or_b32 v20, v20, s52, v5
	s_waitcnt lgkmcnt(3)
	v_bfe_u32 v5, v30, 16, 1
	v_add3_u32 v5, v30, v5, s51
	s_waitcnt lgkmcnt(2)
	v_bfe_u32 v21, v32, 16, 1
	ds_read2_b32 v[38:39], v9 offset0:214 offset1:222
	v_lshrrev_b32_e32 v5, 16, v5
	v_add3_u32 v21, v32, v21, s51
	ds_read2_b32 v[40:41], v9 offset0:247 offset1:255
	v_and_or_b32 v21, v21, s52, v5
	s_waitcnt lgkmcnt(3)
	v_bfe_u32 v5, v34, 16, 1
	v_add3_u32 v5, v34, v5, s51
	s_waitcnt lgkmcnt(2)
	v_bfe_u32 v22, v36, 16, 1
	v_lshrrev_b32_e32 v5, 16, v5
	v_add3_u32 v22, v36, v22, s51
	v_and_or_b32 v22, v22, s52, v5
	s_waitcnt lgkmcnt(1)
	v_bfe_u32 v5, v38, 16, 1
	v_add3_u32 v5, v38, v5, s51
	s_waitcnt lgkmcnt(0)
	v_bfe_u32 v23, v40, 16, 1
	v_lshrrev_b32_e32 v5, 16, v5
	v_add3_u32 v23, v40, v23, s51
	v_and_or_b32 v23, v23, s52, v5
	v_or_b32_e32 v5, s30, v11
	v_lshlrev_b32_e32 v42, 8, v5
	v_mov_b32_e32 v43, v3
	v_lshl_add_u64 v[42:43], v[26:27], 0, v[42:43]
	v_bfe_u32 v5, v29, 16, 1
	global_store_dwordx4 v[42:43], v[20:23], off sc1
	v_add3_u32 v5, v29, v5, s51
	v_lshrrev_b32_e32 v5, 16, v5
	v_bfe_u32 v20, v25, 16, 1
	v_add3_u32 v20, v25, v20, s51
	v_and_or_b32 v20, v20, s52, v5
	v_bfe_u32 v5, v31, 16, 1
	v_add3_u32 v5, v31, v5, s51
	v_bfe_u32 v21, v33, 16, 1
	v_lshrrev_b32_e32 v5, 16, v5
	v_add3_u32 v21, v33, v21, s51
	v_and_or_b32 v21, v21, s52, v5
	v_bfe_u32 v5, v35, 16, 1
	v_add3_u32 v5, v35, v5, s51
	v_bfe_u32 v22, v37, 16, 1
	v_lshrrev_b32_e32 v5, 16, v5
	v_add3_u32 v22, v37, v22, s51
	v_and_or_b32 v22, v22, s52, v5
	v_bfe_u32 v5, v39, 16, 1
	v_add3_u32 v5, v39, v5, s51
	v_bfe_u32 v23, v41, 16, 1
	v_lshrrev_b32_e32 v5, 16, v5
	v_add3_u32 v23, v41, v23, s51
	v_and_or_b32 v23, v23, s52, v5
	v_or_b32_e32 v5, s30, v12
	v_lshlrev_b32_e32 v24, 8, v5
	v_mov_b32_e32 v25, v3
	v_lshl_add_u64 v[24:25], v[26:27], 0, v[24:25]
	global_store_dwordx4 v[24:25], v[20:23], off sc1
	s_waitcnt lgkmcnt(0)
	s_mov_b64 s[36:37], 0
.LBB0_28:
	s_andn2_b64 vcc, exec, s[36:37]
	s_cbranch_vccnz .LBB0_30
	s_ashr_i32 s35, s34, 31
	s_lshl_b64 s[36:37], s[34:35], 22
	s_waitcnt lgkmcnt(0)
	s_add_u32 s92, s28, s36
	s_addc_u32 s93, s29, s37
	s_lshl_b64 s[36:37], s[34:35], 21
	s_add_u32 s36, s39, s36
	s_mul_i32 s30, s34, 0xffffd7c0
	s_addc_u32 s35, s40, s37
	s_add_i32 s30, s45, s30
	s_add_i32 s30, s30, 0x1dc00
	s_and_b32 s37, s30, 0x1ffc0
	s_and_b32 s30, s43, 0x3e0
	s_lshl_b32 s94, s30, 2
	s_add_u32 s92, s92, s94
	v_or_b32_e32 v5, s37, v6
	s_addc_u32 s93, s93, 0
	v_lshl_add_u64 v[20:21], s[92:93], 0, v[2:3]
	v_lshlrev_b32_e32 v22, 12, v5
	v_mov_b32_e32 v23, v3
	v_lshl_add_u64 v[20:21], v[20:21], 0, v[22:23]
	v_add_co_u32_e32 v22, vcc, s47, v20
	s_lshl_b32 s37, s37, 1
	s_nop 0
	v_addc_co_u32_e32 v23, vcc, 0, v21, vcc
	v_add_co_u32_e32 v24, vcc, s48, v20
	s_add_u32 s36, s36, s37
	s_nop 0
	v_addc_co_u32_e32 v25, vcc, 0, v21, vcc
	v_add_co_u32_e32 v26, vcc, s49, v20
	s_addc_u32 s37, s35, 0
	s_nop 0
	v_addc_co_u32_e32 v27, vcc, 0, v21, vcc
	v_add_co_u32_e32 v28, vcc, s53, v20
	s_nop 1
	v_addc_co_u32_e32 v29, vcc, 0, v21, vcc
	v_add_co_u32_e32 v30, vcc, s56, v20
	s_nop 1
	v_addc_co_u32_e32 v31, vcc, 0, v21, vcc
	v_add_co_u32_e32 v32, vcc, s57, v20
	s_nop 1
	v_addc_co_u32_e32 v33, vcc, 0, v21, vcc
	v_add_co_u32_e32 v34, vcc, s58, v20
	s_nop 1
	v_addc_co_u32_e32 v35, vcc, 0, v21, vcc
	global_load_dword v5, v[20:21], off nt
	global_load_dword v38, v[22:23], off nt
	global_load_dword v39, v[24:25], off nt
	global_load_dword v40, v[26:27], off nt
	global_load_dword v41, v[28:29], off nt
	global_load_dword v42, v[30:31], off nt
	global_load_dword v43, v[32:33], off nt
	global_load_dword v44, v[34:35], off nt
	v_add_co_u32_e32 v22, vcc, s59, v20
	s_nop 1
	v_addc_co_u32_e32 v23, vcc, 0, v21, vcc
	v_add_co_u32_e32 v24, vcc, s60, v20
	s_nop 1
	v_addc_co_u32_e32 v25, vcc, 0, v21, vcc
	v_add_co_u32_e32 v26, vcc, s61, v20
	s_nop 1
	v_addc_co_u32_e32 v27, vcc, 0, v21, vcc
	v_add_co_u32_e32 v28, vcc, s62, v20
	s_nop 1
	v_addc_co_u32_e32 v29, vcc, 0, v21, vcc
	v_add_co_u32_e32 v30, vcc, s63, v20
	s_nop 1
	v_addc_co_u32_e32 v31, vcc, 0, v21, vcc
	v_add_co_u32_e32 v32, vcc, s64, v20
	s_nop 1
	v_addc_co_u32_e32 v33, vcc, 0, v21, vcc
	v_add_co_u32_e32 v34, vcc, s65, v20
	s_nop 1
	v_addc_co_u32_e32 v35, vcc, 0, v21, vcc
	v_add_co_u32_e32 v36, vcc, s66, v20
	s_nop 1
	v_addc_co_u32_e32 v37, vcc, 0, v21, vcc
	global_load_dword v45, v[22:23], off nt
	global_load_dword v46, v[24:25], off nt
	global_load_dword v47, v[26:27], off nt
	global_load_dword v48, v[28:29], off nt
	global_load_dword v49, v[30:31], off nt
	global_load_dword v50, v[32:33], off nt
	global_load_dword v51, v[34:35], off nt
	global_load_dword v52, v[36:37], off nt
	v_add_co_u32_e32 v22, vcc, s67, v20
	s_nop 1
	v_addc_co_u32_e32 v23, vcc, 0, v21, vcc
	v_add_co_u32_e32 v24, vcc, s68, v20
	s_nop 1
	v_addc_co_u32_e32 v25, vcc, 0, v21, vcc
	v_add_co_u32_e32 v26, vcc, s69, v20
	s_nop 1
	v_addc_co_u32_e32 v27, vcc, 0, v21, vcc
	v_add_co_u32_e32 v28, vcc, s70, v20
	s_nop 1
	v_addc_co_u32_e32 v29, vcc, 0, v21, vcc
	v_add_co_u32_e32 v30, vcc, s71, v20
	s_nop 1
	v_addc_co_u32_e32 v31, vcc, 0, v21, vcc
	v_add_co_u32_e32 v32, vcc, s72, v20
	s_nop 1
	v_addc_co_u32_e32 v33, vcc, 0, v21, vcc
	v_add_co_u32_e32 v34, vcc, s73, v20
	s_nop 1
	v_addc_co_u32_e32 v35, vcc, 0, v21, vcc
	v_add_co_u32_e32 v36, vcc, s74, v20
	s_nop 1
	v_addc_co_u32_e32 v37, vcc, 0, v21, vcc
	global_load_dword v53, v[22:23], off nt
	global_load_dword v54, v[24:25], off nt
	global_load_dword v55, v[26:27], off nt
	global_load_dword v56, v[28:29], off nt
	global_load_dword v57, v[30:31], off nt
	global_load_dword v58, v[32:33], off nt
	global_load_dword v59, v[34:35], off nt
	s_nop 0
	global_load_dword v36, v[36:37], off nt
	v_add_co_u32_e32 v22, vcc, s75, v20
	s_nop 1
	v_addc_co_u32_e32 v23, vcc, 0, v21, vcc
	v_add_co_u32_e32 v24, vcc, s76, v20
	s_nop 1
	v_addc_co_u32_e32 v25, vcc, 0, v21, vcc
	v_add_co_u32_e32 v26, vcc, s77, v20
	s_nop 1
	v_addc_co_u32_e32 v27, vcc, 0, v21, vcc
	v_add_co_u32_e32 v28, vcc, s78, v20
	s_nop 1
	v_addc_co_u32_e32 v29, vcc, 0, v21, vcc
	v_add_co_u32_e32 v30, vcc, s79, v20
	s_nop 1
	v_addc_co_u32_e32 v31, vcc, 0, v21, vcc
	v_add_co_u32_e32 v32, vcc, s80, v20
	s_nop 1
	v_addc_co_u32_e32 v33, vcc, 0, v21, vcc
	v_add_co_u32_e32 v34, vcc, s81, v20
	s_nop 1
	v_addc_co_u32_e32 v35, vcc, 0, v21, vcc
	v_add_co_u32_e32 v20, vcc, s82, v20
	s_nop 1
	v_addc_co_u32_e32 v21, vcc, 0, v21, vcc
	global_load_dword v22, v[22:23], off nt
	s_nop 0
	global_load_dword v23, v[24:25], off nt
	s_nop 0
	global_load_dword v24, v[26:27], off nt
	global_load_dword v25, v[28:29], off nt
	s_nop 0
	global_load_dword v26, v[30:31], off nt
	global_load_dword v27, v[32:33], off nt
	global_load_dword v28, v[34:35], off nt
	s_nop 0
	global_load_dword v20, v[20:21], off nt
	s_waitcnt vmcnt(30)
	ds_write2_b32 v7, v5, v38 offset1:66
	s_waitcnt vmcnt(28)
	ds_write2_b32 v7, v39, v40 offset0:132 offset1:198
	s_waitcnt vmcnt(26)
	ds_write2_b32 v13, v41, v42 offset0:8 offset1:74
	s_waitcnt vmcnt(24)
	ds_write2_b32 v13, v43, v44 offset0:140 offset1:206
	s_waitcnt vmcnt(22)
	ds_write2_b32 v14, v45, v46 offset0:16 offset1:82
	s_waitcnt vmcnt(20)
	ds_write2_b32 v14, v47, v48 offset0:148 offset1:214
	s_waitcnt vmcnt(18)
	ds_write2_b32 v15, v49, v50 offset0:24 offset1:90
	s_waitcnt vmcnt(16)
	ds_write2_b32 v15, v51, v52 offset0:156 offset1:222
	s_waitcnt vmcnt(14)
	ds_write2_b32 v16, v53, v54 offset0:32 offset1:98
	s_waitcnt vmcnt(12)
	ds_write2_b32 v16, v55, v56 offset0:164 offset1:230
	s_waitcnt vmcnt(10)
	ds_write2_b32 v17, v57, v58 offset0:40 offset1:106
	s_waitcnt vmcnt(8)
	ds_write2_b32 v17, v59, v36 offset0:172 offset1:238
	s_waitcnt vmcnt(6)
	ds_write2_b32 v18, v22, v23 offset0:48 offset1:114
	s_waitcnt vmcnt(4)
	ds_write2_b32 v18, v24, v25 offset0:180 offset1:246
	s_waitcnt vmcnt(2)
	ds_write2_b32 v19, v26, v27 offset0:56 offset1:122
	s_waitcnt vmcnt(0)
	ds_write2_b32 v19, v28, v20 offset0:188 offset1:254
	s_waitcnt lgkmcnt(0)
	ds_read2_b32 v[24:25], v9 offset1:8
	ds_read2_b32 v[28:29], v9 offset0:33 offset1:41
	ds_read2_b32 v[30:31], v9 offset0:66 offset1:74
	v_mov_b32_e32 v5, v3
	ds_read2_b32 v[32:33], v9 offset0:99 offset1:107
	v_lshl_add_u64 v[26:27], s[36:37], 0, v[4:5]
	s_waitcnt lgkmcnt(3)
	v_bfe_u32 v5, v24, 16, 1
	v_add3_u32 v5, v24, v5, s51
	s_waitcnt lgkmcnt(2)
	v_bfe_u32 v20, v28, 16, 1
	ds_read2_b32 v[34:35], v9 offset0:132 offset1:140
	v_lshrrev_b32_e32 v5, 16, v5
	v_add3_u32 v20, v28, v20, s51
	ds_read2_b32 v[36:37], v9 offset0:165 offset1:173
	v_and_or_b32 v20, v20, s52, v5
	s_waitcnt lgkmcnt(3)
	v_bfe_u32 v5, v30, 16, 1
	v_add3_u32 v5, v30, v5, s51
	s_waitcnt lgkmcnt(2)
	v_bfe_u32 v21, v32, 16, 1
	ds_read2_b32 v[38:39], v9 offset0:198 offset1:206
	v_lshrrev_b32_e32 v5, 16, v5
	v_add3_u32 v21, v32, v21, s51
	ds_read2_b32 v[40:41], v9 offset0:231 offset1:239
	v_and_or_b32 v21, v21, s52, v5
	s_waitcnt lgkmcnt(3)
	v_bfe_u32 v5, v34, 16, 1
	v_add3_u32 v5, v34, v5, s51
	s_waitcnt lgkmcnt(2)
	v_bfe_u32 v22, v36, 16, 1
	v_lshrrev_b32_e32 v5, 16, v5
	v_add3_u32 v22, v36, v22, s51
	v_and_or_b32 v22, v22, s52, v5
	s_waitcnt lgkmcnt(1)
	v_bfe_u32 v5, v38, 16, 1
	v_add3_u32 v5, v38, v5, s51
	s_waitcnt lgkmcnt(0)
	v_bfe_u32 v23, v40, 16, 1
	v_lshrrev_b32_e32 v5, 16, v5
	v_add3_u32 v23, v40, v23, s51
	v_and_or_b32 v23, v23, s52, v5
	v_or_b32_e32 v5, s30, v8
	v_lshlrev_b32_e32 v42, 11, v5
	v_mov_b32_e32 v43, v3
	v_lshl_add_u64 v[42:43], v[26:27], 0, v[42:43]
	v_bfe_u32 v5, v25, 16, 1
	global_store_dwordx4 v[42:43], v[20:23], off sc1
	v_add3_u32 v5, v25, v5, s51
	v_lshrrev_b32_e32 v5, 16, v5
	v_bfe_u32 v20, v29, 16, 1
	v_add3_u32 v20, v29, v20, s51
	v_and_or_b32 v20, v20, s52, v5
	v_bfe_u32 v5, v31, 16, 1
	v_add3_u32 v5, v31, v5, s51
	v_bfe_u32 v21, v33, 16, 1
	v_lshrrev_b32_e32 v5, 16, v5
	v_add3_u32 v21, v33, v21, s51
	v_and_or_b32 v21, v21, s52, v5
	v_bfe_u32 v5, v35, 16, 1
	v_add3_u32 v5, v35, v5, s51
	v_bfe_u32 v22, v37, 16, 1
	v_lshrrev_b32_e32 v5, 16, v5
	v_add3_u32 v22, v37, v22, s51
	v_and_or_b32 v22, v22, s52, v5
	v_bfe_u32 v5, v39, 16, 1
	v_add3_u32 v5, v39, v5, s51
	v_bfe_u32 v23, v41, 16, 1
	v_lshrrev_b32_e32 v5, 16, v5
	v_add3_u32 v23, v41, v23, s51
	v_and_or_b32 v23, v23, s52, v5
	v_or_b32_e32 v5, s30, v10
	v_lshlrev_b32_e32 v24, 11, v5
	v_mov_b32_e32 v25, v3
	ds_read2_b32 v[28:29], v9 offset0:16 offset1:24
	v_lshl_add_u64 v[24:25], v[26:27], 0, v[24:25]
	global_store_dwordx4 v[24:25], v[20:23], off sc1
	ds_read2_b32 v[24:25], v9 offset0:49 offset1:57
	ds_read2_b32 v[30:31], v9 offset0:82 offset1:90
	ds_read2_b32 v[32:33], v9 offset0:115 offset1:123
	s_waitcnt lgkmcnt(3)
	v_bfe_u32 v5, v28, 16, 1
	v_add3_u32 v5, v28, v5, s51
	s_waitcnt lgkmcnt(2)
	v_bfe_u32 v20, v24, 16, 1
	ds_read2_b32 v[34:35], v9 offset0:148 offset1:156
	v_lshrrev_b32_e32 v5, 16, v5
	v_add3_u32 v20, v24, v20, s51
	ds_read2_b32 v[36:37], v9 offset0:181 offset1:189
	v_and_or_b32 v20, v20, s52, v5
	s_waitcnt lgkmcnt(3)
	v_bfe_u32 v5, v30, 16, 1
	v_add3_u32 v5, v30, v5, s51
	s_waitcnt lgkmcnt(2)
	v_bfe_u32 v21, v32, 16, 1
	ds_read2_b32 v[38:39], v9 offset0:214 offset1:222
	v_lshrrev_b32_e32 v5, 16, v5
	v_add3_u32 v21, v32, v21, s51
	ds_read2_b32 v[40:41], v9 offset0:247 offset1:255
	v_and_or_b32 v21, v21, s52, v5
	s_waitcnt lgkmcnt(3)
	v_bfe_u32 v5, v34, 16, 1
	v_add3_u32 v5, v34, v5, s51
	s_waitcnt lgkmcnt(2)
	v_bfe_u32 v22, v36, 16, 1
	v_lshrrev_b32_e32 v5, 16, v5
	v_add3_u32 v22, v36, v22, s51
	v_and_or_b32 v22, v22, s52, v5
	s_waitcnt lgkmcnt(1)
	v_bfe_u32 v5, v38, 16, 1
	v_add3_u32 v5, v38, v5, s51
	s_waitcnt lgkmcnt(0)
	v_bfe_u32 v23, v40, 16, 1
	v_lshrrev_b32_e32 v5, 16, v5
	v_add3_u32 v23, v40, v23, s51
	v_and_or_b32 v23, v23, s52, v5
	v_or_b32_e32 v5, s30, v11
	v_lshlrev_b32_e32 v42, 11, v5
	v_mov_b32_e32 v43, v3
	v_lshl_add_u64 v[42:43], v[26:27], 0, v[42:43]
	v_bfe_u32 v5, v29, 16, 1
	global_store_dwordx4 v[42:43], v[20:23], off sc1
	v_add3_u32 v5, v29, v5, s51
	v_lshrrev_b32_e32 v5, 16, v5
	v_bfe_u32 v20, v25, 16, 1
	v_add3_u32 v20, v25, v20, s51
	v_and_or_b32 v20, v20, s52, v5
	v_bfe_u32 v5, v31, 16, 1
	v_add3_u32 v5, v31, v5, s51
	v_bfe_u32 v21, v33, 16, 1
	v_lshrrev_b32_e32 v5, 16, v5
	v_add3_u32 v21, v33, v21, s51
	v_and_or_b32 v21, v21, s52, v5
	v_bfe_u32 v5, v35, 16, 1
	v_add3_u32 v5, v35, v5, s51
	v_bfe_u32 v22, v37, 16, 1
	v_lshrrev_b32_e32 v5, 16, v5
	v_add3_u32 v22, v37, v22, s51
	v_and_or_b32 v22, v22, s52, v5
	v_bfe_u32 v5, v39, 16, 1
	v_add3_u32 v5, v39, v5, s51
	v_bfe_u32 v23, v41, 16, 1
	v_lshrrev_b32_e32 v5, 16, v5
	v_add3_u32 v23, v41, v23, s51
	v_and_or_b32 v23, v23, s52, v5
	v_or_b32_e32 v5, s30, v12
	v_lshlrev_b32_e32 v24, 11, v5
	v_mov_b32_e32 v25, v3
	v_lshl_add_u64 v[24:25], v[26:27], 0, v[24:25]
	global_store_dwordx4 v[24:25], v[20:23], off sc1
	s_waitcnt lgkmcnt(0)

.LBB0_31:
	s_andn2_b64 vcc, exec, s[36:37]
	s_cbranch_vccnz .LBB0_33
	s_add_i32 s30, s91, 0xfffff100
	s_lshr_b32 s35, s30, 8
	s_mul_i32 s36, s34, 3
	s_mul_hi_i32 s30, s34, 3
	s_add_u32 s36, s36, s35
	s_addc_u32 s37, s30, 0
	s_lshl_b64 s[36:37], s[36:37], 21
	s_waitcnt lgkmcnt(0)
	s_add_u32 s93, s4, s36
	s_addc_u32 s95, s5, s37
	s_mul_i32 s36, s34, 0x300000
	s_mul_hi_i32 s30, s34, 0x300000
	s_add_u32 s36, s19, s36
	s_addc_u32 s37, s38, s30
	s_lshl_b32 s30, s34, 6
	s_sub_i32 s30, s45, s30
	s_and_b32 s92, s30, 0x1c0
	s_and_b32 s30, s43, 0x3e0
	s_lshl_b32 s94, s30, 2
	s_add_u32 s94, s93, s94
	v_or_b32_e32 v5, s92, v6
	s_addc_u32 s95, s95, 0
	v_lshl_add_u64 v[20:21], s[94:95], 0, v[2:3]
	v_lshlrev_b32_e32 v22, 12, v5
	v_mov_b32_e32 v23, v3
	v_lshl_add_u64 v[20:21], v[20:21], 0, v[22:23]
	v_add_co_u32_e32 v22, vcc, s47, v20
	s_lshl_b32 s35, s35, 10
	s_nop 0
	v_addc_co_u32_e32 v23, vcc, 0, v21, vcc
	v_add_co_u32_e32 v24, vcc, s48, v20
	s_add_u32 s35, s36, s35
	s_nop 0
	v_addc_co_u32_e32 v25, vcc, 0, v21, vcc
	v_add_co_u32_e32 v26, vcc, s49, v20
	s_addc_u32 s37, s37, 0
	s_nop 0
	v_addc_co_u32_e32 v27, vcc, 0, v21, vcc
	v_add_co_u32_e32 v28, vcc, s53, v20
	s_lshl_b32 s36, s92, 1
	s_nop 0
	v_addc_co_u32_e32 v29, vcc, 0, v21, vcc
	v_add_co_u32_e32 v30, vcc, s56, v20
	s_add_u32 s36, s35, s36
	s_nop 0
	v_addc_co_u32_e32 v31, vcc, 0, v21, vcc
	v_add_co_u32_e32 v32, vcc, s57, v20
	s_addc_u32 s37, s37, 0
	s_nop 0
	v_addc_co_u32_e32 v33, vcc, 0, v21, vcc
	v_add_co_u32_e32 v34, vcc, s58, v20
	s_nop 1
	v_addc_co_u32_e32 v35, vcc, 0, v21, vcc
	global_load_dword v5, v[20:21], off nt
	global_load_dword v38, v[22:23], off nt
	global_load_dword v39, v[24:25], off nt
	global_load_dword v40, v[26:27], off nt
	global_load_dword v41, v[28:29], off nt
	global_load_dword v42, v[30:31], off nt
	global_load_dword v43, v[32:33], off nt
	global_load_dword v44, v[34:35], off nt
	v_add_co_u32_e32 v22, vcc, s59, v20
	s_nop 1
	v_addc_co_u32_e32 v23, vcc, 0, v21, vcc
	v_add_co_u32_e32 v24, vcc, s60, v20
	s_nop 1
	v_addc_co_u32_e32 v25, vcc, 0, v21, vcc
	v_add_co_u32_e32 v26, vcc, s61, v20
	s_nop 1
	v_addc_co_u32_e32 v27, vcc, 0, v21, vcc
	v_add_co_u32_e32 v28, vcc, s62, v20
	s_nop 1
	v_addc_co_u32_e32 v29, vcc, 0, v21, vcc
	v_add_co_u32_e32 v30, vcc, s63, v20
	s_nop 1
	v_addc_co_u32_e32 v31, vcc, 0, v21, vcc
	v_add_co_u32_e32 v32, vcc, s64, v20
	s_nop 1
	v_addc_co_u32_e32 v33, vcc, 0, v21, vcc
	v_add_co_u32_e32 v34, vcc, s65, v20
	s_nop 1
	v_addc_co_u32_e32 v35, vcc, 0, v21, vcc
	v_add_co_u32_e32 v36, vcc, s66, v20
	s_nop 1
	v_addc_co_u32_e32 v37, vcc, 0, v21, vcc
	global_load_dword v45, v[22:23], off nt
	global_load_dword v46, v[24:25], off nt
	global_load_dword v47, v[26:27], off nt
	global_load_dword v48, v[28:29], off nt
	global_load_dword v49, v[30:31], off nt
	global_load_dword v50, v[32:33], off nt
	global_load_dword v51, v[34:35], off nt
	global_load_dword v52, v[36:37], off nt
	v_add_co_u32_e32 v22, vcc, s67, v20
	s_nop 1
	v_addc_co_u32_e32 v23, vcc, 0, v21, vcc
	v_add_co_u32_e32 v24, vcc, s68, v20
	s_nop 1
	v_addc_co_u32_e32 v25, vcc, 0, v21, vcc
	v_add_co_u32_e32 v26, vcc, s69, v20
	s_nop 1
	v_addc_co_u32_e32 v27, vcc, 0, v21, vcc
	v_add_co_u32_e32 v28, vcc, s70, v20
	s_nop 1
	v_addc_co_u32_e32 v29, vcc, 0, v21, vcc
	v_add_co_u32_e32 v30, vcc, s71, v20
	s_nop 1
	v_addc_co_u32_e32 v31, vcc, 0, v21, vcc
	v_add_co_u32_e32 v32, vcc, s72, v20
	s_nop 1
	v_addc_co_u32_e32 v33, vcc, 0, v21, vcc
	v_add_co_u32_e32 v34, vcc, s73, v20
	s_nop 1
	v_addc_co_u32_e32 v35, vcc, 0, v21, vcc
	v_add_co_u32_e32 v36, vcc, s74, v20
	s_nop 1
	v_addc_co_u32_e32 v37, vcc, 0, v21, vcc
	global_load_dword v53, v[22:23], off nt
	global_load_dword v54, v[24:25], off nt
	global_load_dword v55, v[26:27], off nt
	global_load_dword v56, v[28:29], off nt
	global_load_dword v57, v[30:31], off nt
	global_load_dword v58, v[32:33], off nt
	global_load_dword v59, v[34:35], off nt
	s_nop 0
	global_load_dword v36, v[36:37], off nt
	v_add_co_u32_e32 v22, vcc, s75, v20
	s_nop 1
	v_addc_co_u32_e32 v23, vcc, 0, v21, vcc
	v_add_co_u32_e32 v24, vcc, s76, v20
	s_nop 1
	v_addc_co_u32_e32 v25, vcc, 0, v21, vcc
	v_add_co_u32_e32 v26, vcc, s77, v20
	s_nop 1
	v_addc_co_u32_e32 v27, vcc, 0, v21, vcc
	v_add_co_u32_e32 v28, vcc, s78, v20
	s_nop 1
	v_addc_co_u32_e32 v29, vcc, 0, v21, vcc
	v_add_co_u32_e32 v30, vcc, s79, v20
	s_nop 1
	v_addc_co_u32_e32 v31, vcc, 0, v21, vcc
	v_add_co_u32_e32 v32, vcc, s80, v20
	s_nop 1
	v_addc_co_u32_e32 v33, vcc, 0, v21, vcc
	v_add_co_u32_e32 v34, vcc, s81, v20
	s_nop 1
	v_addc_co_u32_e32 v35, vcc, 0, v21, vcc
	v_add_co_u32_e32 v20, vcc, s82, v20
	s_nop 1
	v_addc_co_u32_e32 v21, vcc, 0, v21, vcc
	global_load_dword v22, v[22:23], off nt
	s_nop 0
	global_load_dword v23, v[24:25], off nt
	s_nop 0
	global_load_dword v24, v[26:27], off nt
	global_load_dword v25, v[28:29], off nt
	s_nop 0
	global_load_dword v26, v[30:31], off nt
	global_load_dword v27, v[32:33], off nt
	global_load_dword v28, v[34:35], off nt
	s_nop 0
	global_load_dword v20, v[20:21], off nt
	s_waitcnt vmcnt(30)
	ds_write2_b32 v7, v5, v38 offset1:66
	s_waitcnt vmcnt(28)
	ds_write2_b32 v7, v39, v40 offset0:132 offset1:198
	s_waitcnt vmcnt(26)
	ds_write2_b32 v13, v41, v42 offset0:8 offset1:74
	s_waitcnt vmcnt(24)
	ds_write2_b32 v13, v43, v44 offset0:140 offset1:206
	s_waitcnt vmcnt(22)
	ds_write2_b32 v14, v45, v46 offset0:16 offset1:82
	s_waitcnt vmcnt(20)
	ds_write2_b32 v14, v47, v48 offset0:148 offset1:214
	s_waitcnt vmcnt(18)
	ds_write2_b32 v15, v49, v50 offset0:24 offset1:90
	s_waitcnt vmcnt(16)
	ds_write2_b32 v15, v51, v52 offset0:156 offset1:222
	s_waitcnt vmcnt(14)
	ds_write2_b32 v16, v53, v54 offset0:32 offset1:98
	s_waitcnt vmcnt(12)
	ds_write2_b32 v16, v55, v56 offset0:164 offset1:230
	s_waitcnt vmcnt(10)
	ds_write2_b32 v17, v57, v58 offset0:40 offset1:106
	s_waitcnt vmcnt(8)
	ds_write2_b32 v17, v59, v36 offset0:172 offset1:238
	s_waitcnt vmcnt(6)
	ds_write2_b32 v18, v22, v23 offset0:48 offset1:114
	s_waitcnt vmcnt(4)
	ds_write2_b32 v18, v24, v25 offset0:180 offset1:246
	s_waitcnt vmcnt(2)
	ds_write2_b32 v19, v26, v27 offset0:56 offset1:122
	s_waitcnt vmcnt(0)
	ds_write2_b32 v19, v28, v20 offset0:188 offset1:254
	s_waitcnt lgkmcnt(0)
	ds_read2_b32 v[24:25], v9 offset1:8
	ds_read2_b32 v[28:29], v9 offset0:33 offset1:41
	ds_read2_b32 v[30:31], v9 offset0:66 offset1:74
	v_mov_b32_e32 v5, v3
	ds_read2_b32 v[32:33], v9 offset0:99 offset1:107
	v_lshl_add_u64 v[26:27], s[36:37], 0, v[4:5]
	s_waitcnt lgkmcnt(3)
	v_bfe_u32 v5, v24, 16, 1
	v_add3_u32 v5, v24, v5, s51
	s_waitcnt lgkmcnt(2)
	v_bfe_u32 v20, v28, 16, 1
	ds_read2_b32 v[34:35], v9 offset0:132 offset1:140
	v_lshrrev_b32_e32 v5, 16, v5
	v_add3_u32 v20, v28, v20, s51
	ds_read2_b32 v[36:37], v9 offset0:165 offset1:173
	v_and_or_b32 v20, v20, s52, v5
	s_waitcnt lgkmcnt(3)
	v_bfe_u32 v5, v30, 16, 1
	v_add3_u32 v5, v30, v5, s51
	s_waitcnt lgkmcnt(2)
	v_bfe_u32 v21, v32, 16, 1
	ds_read2_b32 v[38:39], v9 offset0:198 offset1:206
	v_lshrrev_b32_e32 v5, 16, v5
	v_add3_u32 v21, v32, v21, s51
	ds_read2_b32 v[40:41], v9 offset0:231 offset1:239
	v_and_or_b32 v21, v21, s52, v5
	s_waitcnt lgkmcnt(3)
	v_bfe_u32 v5, v34, 16, 1
	v_add3_u32 v5, v34, v5, s51
	s_waitcnt lgkmcnt(2)
	v_bfe_u32 v22, v36, 16, 1
	v_lshrrev_b32_e32 v5, 16, v5
	v_add3_u32 v22, v36, v22, s51
	v_and_or_b32 v22, v22, s52, v5
	s_waitcnt lgkmcnt(1)
	v_bfe_u32 v5, v38, 16, 1
	v_add3_u32 v5, v38, v5, s51
	s_waitcnt lgkmcnt(0)
	v_bfe_u32 v23, v40, 16, 1
	v_lshrrev_b32_e32 v5, 16, v5
	v_add3_u32 v23, v40, v23, s51
	v_and_or_b32 v23, v23, s52, v5
	v_or_b32_e32 v5, s30, v8
	v_mul_u32_u24_e32 v5, 0x600, v5
	v_lshlrev_b32_e32 v42, 1, v5
	v_mov_b32_e32 v43, v3
	v_lshl_add_u64 v[42:43], v[26:27], 0, v[42:43]
	v_bfe_u32 v5, v25, 16, 1
	global_store_dwordx4 v[42:43], v[20:23], off sc1
	v_add3_u32 v5, v25, v5, s51
	v_lshrrev_b32_e32 v5, 16, v5
	v_bfe_u32 v20, v29, 16, 1
	v_add3_u32 v20, v29, v20, s51
	v_and_or_b32 v20, v20, s52, v5
	v_bfe_u32 v5, v31, 16, 1
	v_add3_u32 v5, v31, v5, s51
	v_bfe_u32 v21, v33, 16, 1
	v_lshrrev_b32_e32 v5, 16, v5
	v_add3_u32 v21, v33, v21, s51
	v_and_or_b32 v21, v21, s52, v5
	v_bfe_u32 v5, v35, 16, 1
	v_add3_u32 v5, v35, v5, s51
	v_bfe_u32 v22, v37, 16, 1
	v_lshrrev_b32_e32 v5, 16, v5
	v_add3_u32 v22, v37, v22, s51
	v_and_or_b32 v22, v22, s52, v5
	v_bfe_u32 v5, v39, 16, 1
	v_add3_u32 v5, v39, v5, s51
	v_bfe_u32 v23, v41, 16, 1
	v_lshrrev_b32_e32 v5, 16, v5
	v_add3_u32 v23, v41, v23, s51
	v_and_or_b32 v23, v23, s52, v5
	v_or_b32_e32 v5, s30, v10
	v_mul_u32_u24_e32 v5, 0x600, v5
	v_lshlrev_b32_e32 v24, 1, v5
	v_mov_b32_e32 v25, v3
	ds_read2_b32 v[28:29], v9 offset0:16 offset1:24
	v_lshl_add_u64 v[24:25], v[26:27], 0, v[24:25]
	global_store_dwordx4 v[24:25], v[20:23], off sc1
	ds_read2_b32 v[24:25], v9 offset0:49 offset1:57
	ds_read2_b32 v[30:31], v9 offset0:82 offset1:90
	ds_read2_b32 v[32:33], v9 offset0:115 offset1:123
	s_waitcnt lgkmcnt(3)
	v_bfe_u32 v5, v28, 16, 1
	v_add3_u32 v5, v28, v5, s51
	s_waitcnt lgkmcnt(2)
	v_bfe_u32 v20, v24, 16, 1
	ds_read2_b32 v[34:35], v9 offset0:148 offset1:156
	v_lshrrev_b32_e32 v5, 16, v5
	v_add3_u32 v20, v24, v20, s51
	ds_read2_b32 v[36:37], v9 offset0:181 offset1:189
	v_and_or_b32 v20, v20, s52, v5
	s_waitcnt lgkmcnt(3)
	v_bfe_u32 v5, v30, 16, 1
	v_add3_u32 v5, v30, v5, s51
	s_waitcnt lgkmcnt(2)
	v_bfe_u32 v21, v32, 16, 1
	ds_read2_b32 v[38:39], v9 offset0:214 offset1:222
	v_lshrrev_b32_e32 v5, 16, v5
	v_add3_u32 v21, v32, v21, s51
	ds_read2_b32 v[40:41], v9 offset0:247 offset1:255
	v_and_or_b32 v21, v21, s52, v5
	s_waitcnt lgkmcnt(3)
	v_bfe_u32 v5, v34, 16, 1
	v_add3_u32 v5, v34, v5, s51
	s_waitcnt lgkmcnt(2)
	v_bfe_u32 v22, v36, 16, 1
	v_lshrrev_b32_e32 v5, 16, v5
	v_add3_u32 v22, v36, v22, s51
	v_and_or_b32 v22, v22, s52, v5
	s_waitcnt lgkmcnt(1)
	v_bfe_u32 v5, v38, 16, 1
	v_add3_u32 v5, v38, v5, s51
	s_waitcnt lgkmcnt(0)
	v_bfe_u32 v23, v40, 16, 1
	v_lshrrev_b32_e32 v5, 16, v5
	v_add3_u32 v23, v40, v23, s51
	v_and_or_b32 v23, v23, s52, v5
	v_or_b32_e32 v5, s30, v11
	v_mul_u32_u24_e32 v5, 0x600, v5
	v_lshlrev_b32_e32 v42, 1, v5
	v_mov_b32_e32 v43, v3
	v_lshl_add_u64 v[42:43], v[26:27], 0, v[42:43]
	v_bfe_u32 v5, v29, 16, 1
	global_store_dwordx4 v[42:43], v[20:23], off sc1
	v_add3_u32 v5, v29, v5, s51
	v_lshrrev_b32_e32 v5, 16, v5
	v_bfe_u32 v20, v25, 16, 1
	v_add3_u32 v20, v25, v20, s51
	v_and_or_b32 v20, v20, s52, v5
	v_bfe_u32 v5, v31, 16, 1
	v_add3_u32 v5, v31, v5, s51
	v_bfe_u32 v21, v33, 16, 1
	v_lshrrev_b32_e32 v5, 16, v5
	v_add3_u32 v21, v33, v21, s51
	v_and_or_b32 v21, v21, s52, v5
	v_bfe_u32 v5, v35, 16, 1
	v_add3_u32 v5, v35, v5, s51
	v_bfe_u32 v22, v37, 16, 1
	v_lshrrev_b32_e32 v5, 16, v5
	v_add3_u32 v22, v37, v22, s51
	v_and_or_b32 v22, v22, s52, v5
	v_bfe_u32 v5, v39, 16, 1
	v_add3_u32 v5, v39, v5, s51
	v_bfe_u32 v23, v41, 16, 1
	v_lshrrev_b32_e32 v5, 16, v5
	v_add3_u32 v23, v41, v23, s51
	v_and_or_b32 v23, v23, s52, v5
	v_or_b32_e32 v5, s30, v12
	v_mul_u32_u24_e32 v5, 0x600, v5
	v_lshlrev_b32_e32 v24, 1, v5
	v_mov_b32_e32 v25, v3
	v_lshl_add_u64 v[24:25], v[26:27], 0, v[24:25]
	global_store_dwordx4 v[24:25], v[20:23], off sc1
	s_waitcnt lgkmcnt(0)

.LBB0_34:
	s_andn2_b64 vcc, exec, s[36:37]
	s_cbranch_vccnz .LBB0_36
	s_mul_i32 s35, s34, 0xc00000
	s_mul_hi_i32 s30, s34, 0xc00000
	s_waitcnt lgkmcnt(0)
	s_add_u32 s92, s6, s35
	s_addc_u32 s93, s7, s30
	s_mul_i32 s35, s34, 0xf00000
	s_mul_hi_i32 s30, s34, 0xf00000
	s_add_u32 s35, s20, s35
	s_addc_u32 s36, s21, s30
	s_add_i32 s30, s91, 0xf700
	s_and_b32 s37, s30, 0xffff
	s_mul_i32 s37, s37, 0xaaab
	s_lshr_b32 s94, s37, 16
	s_lshr_b32 s37, s37, 22
	s_mulk_i32 s37, 0x60
	s_sub_i32 s30, s30, s37
	s_lshl_b32 s30, s30, 5
	s_and_b32 s30, s30, 0xffe0
	s_and_b32 s37, s94, 0xffc0
	s_lshl_b32 s94, s30, 2
	v_or_b32_e32 v5, s37, v6
	s_add_u32 s92, s92, s94
	s_addc_u32 s93, s93, 0
	v_mul_u32_u24_e32 v5, 0xc00, v5
	v_lshl_add_u64 v[20:21], s[92:93], 0, v[2:3]
	v_lshlrev_b32_e32 v22, 2, v5
	v_mov_b32_e32 v23, v3
	v_lshl_add_u64 v[20:21], v[20:21], 0, v[22:23]
	v_add_co_u32_e32 v22, vcc, s49, v20
	s_mov_b32 s92, 0x42000
	s_nop 0
	v_addc_co_u32_e32 v23, vcc, 0, v21, vcc
	v_add_co_u32_e32 v24, vcc, s57, v20
	s_lshl_b32 s37, s37, 1
	s_nop 0
	v_addc_co_u32_e32 v25, vcc, 0, v21, vcc
	v_add_co_u32_e32 v26, vcc, s60, v20
	s_nop 1
	v_addc_co_u32_e32 v27, vcc, 0, v21, vcc
	v_add_co_u32_e32 v28, vcc, s63, v20
	s_nop 1
	v_addc_co_u32_e32 v29, vcc, 0, v21, vcc
	v_add_co_u32_e32 v30, vcc, s66, v20
	s_nop 1
	v_addc_co_u32_e32 v31, vcc, 0, v21, vcc
	v_add_co_u32_e32 v32, vcc, s69, v20
	s_nop 1
	v_addc_co_u32_e32 v33, vcc, 0, v21, vcc
	v_add_co_u32_e32 v34, vcc, s72, v20
	s_nop 1
	v_addc_co_u32_e32 v35, vcc, 0, v21, vcc
	global_load_dword v5, v[20:21], off nt
	global_load_dword v38, v[22:23], off nt
	global_load_dword v39, v[24:25], off nt
	global_load_dword v40, v[26:27], off nt
	global_load_dword v41, v[28:29], off nt
	global_load_dword v42, v[30:31], off nt
	global_load_dword v43, v[32:33], off nt
	global_load_dword v44, v[34:35], off nt
	v_add_co_u32_e32 v22, vcc, s75, v20
	s_nop 1
	v_addc_co_u32_e32 v23, vcc, 0, v21, vcc
	v_add_co_u32_e32 v24, vcc, s78, v20
	s_nop 1
	v_addc_co_u32_e32 v25, vcc, 0, v21, vcc
	v_add_co_u32_e32 v26, vcc, s81, v20
	s_nop 1
	v_addc_co_u32_e32 v27, vcc, 0, v21, vcc
	v_add_co_u32_e32 v28, vcc, s92, v20
	s_mov_b32 s92, 0x4e000
	s_nop 0
	v_addc_co_u32_e32 v29, vcc, 0, v21, vcc
	v_add_co_u32_e32 v30, vcc, s83, v20
	s_nop 1
	v_addc_co_u32_e32 v31, vcc, 0, v21, vcc
	v_add_co_u32_e32 v32, vcc, s92, v20
	s_mov_b32 s92, 0x54000
	s_nop 0
	v_addc_co_u32_e32 v33, vcc, 0, v21, vcc
	v_add_co_u32_e32 v34, vcc, s92, v20
	s_mov_b32 s92, 0x60000
	s_nop 0
	v_addc_co_u32_e32 v35, vcc, 0, v21, vcc
	v_add_co_u32_e32 v36, vcc, s84, v20
	s_nop 1
	v_addc_co_u32_e32 v37, vcc, 0, v21, vcc
	global_load_dword v45, v[22:23], off nt
	global_load_dword v46, v[24:25], off nt
	global_load_dword v47, v[26:27], off nt
	global_load_dword v48, v[28:29], off nt
	global_load_dword v49, v[30:31], off nt
	global_load_dword v50, v[32:33], off nt
	global_load_dword v51, v[34:35], off nt
	global_load_dword v52, v[36:37], off nt
	v_add_co_u32_e32 v22, vcc, s92, v20
	s_mov_b32 s92, 0x66000
	s_nop 0
	v_addc_co_u32_e32 v23, vcc, 0, v21, vcc
	v_add_co_u32_e32 v24, vcc, s92, v20
	s_mov_b32 s92, 0x72000
	s_nop 0
	v_addc_co_u32_e32 v25, vcc, 0, v21, vcc
	v_add_co_u32_e32 v26, vcc, s85, v20
	s_nop 1
	v_addc_co_u32_e32 v27, vcc, 0, v21, vcc
	v_add_co_u32_e32 v28, vcc, s92, v20
	s_mov_b32 s92, 0x78000
	s_nop 0
	v_addc_co_u32_e32 v29, vcc, 0, v21, vcc
	v_add_co_u32_e32 v30, vcc, s92, v20
	s_mov_b32 s92, 0x84000
	s_nop 0
	v_addc_co_u32_e32 v31, vcc, 0, v21, vcc
	v_add_co_u32_e32 v32, vcc, s86, v20
	s_nop 1
	v_addc_co_u32_e32 v33, vcc, 0, v21, vcc
	v_add_co_u32_e32 v34, vcc, s92, v20
	s_mov_b32 s92, 0x8a000
	s_nop 0
	v_addc_co_u32_e32 v35, vcc, 0, v21, vcc
	v_add_co_u32_e32 v36, vcc, s92, v20
	s_mov_b32 s92, 0x96000
	s_nop 0
	v_addc_co_u32_e32 v37, vcc, 0, v21, vcc
	global_load_dword v53, v[22:23], off nt
	global_load_dword v54, v[24:25], off nt
	global_load_dword v55, v[26:27], off nt
	global_load_dword v56, v[28:29], off nt
	global_load_dword v57, v[30:31], off nt
	global_load_dword v58, v[32:33], off nt
	global_load_dword v59, v[34:35], off nt
	s_nop 0
	global_load_dword v36, v[36:37], off nt
	v_add_co_u32_e32 v22, vcc, s87, v20
	s_nop 1
	v_addc_co_u32_e32 v23, vcc, 0, v21, vcc
	v_add_co_u32_e32 v24, vcc, s92, v20
	s_mov_b32 s92, 0x9c000
	s_nop 0
	v_addc_co_u32_e32 v25, vcc, 0, v21, vcc
	v_add_co_u32_e32 v26, vcc, s92, v20
	s_mov_b32 s92, 0xa8000
	s_nop 0
	v_addc_co_u32_e32 v27, vcc, 0, v21, vcc
	v_add_co_u32_e32 v28, vcc, s88, v20
	s_nop 1
	v_addc_co_u32_e32 v29, vcc, 0, v21, vcc
	v_add_co_u32_e32 v30, vcc, s92, v20
	s_mov_b32 s92, 0xae000
	s_nop 0
	v_addc_co_u32_e32 v31, vcc, 0, v21, vcc
	v_add_co_u32_e32 v32, vcc, s92, v20
	s_mov_b32 s92, 0xba000
	s_nop 0
	v_addc_co_u32_e32 v33, vcc, 0, v21, vcc
	v_add_co_u32_e32 v34, vcc, s89, v20
	s_nop 1
	v_addc_co_u32_e32 v35, vcc, 0, v21, vcc
	v_add_co_u32_e32 v20, vcc, s92, v20
	s_add_u32 s92, s35, s37
	s_nop 0
	v_addc_co_u32_e32 v21, vcc, 0, v21, vcc
	global_load_dword v22, v[22:23], off nt
	s_nop 0
	global_load_dword v23, v[24:25], off nt
	s_nop 0
	global_load_dword v24, v[26:27], off nt
	global_load_dword v25, v[28:29], off nt
	s_nop 0
	global_load_dword v26, v[30:31], off nt
	global_load_dword v27, v[32:33], off nt
	global_load_dword v28, v[34:35], off nt
	s_nop 0
	global_load_dword v20, v[20:21], off nt
	s_waitcnt vmcnt(30)
	ds_write2_b32 v7, v5, v38 offset1:66
	s_waitcnt vmcnt(28)
	ds_write2_b32 v7, v39, v40 offset0:132 offset1:198
	s_waitcnt vmcnt(26)
	ds_write2_b32 v13, v41, v42 offset0:8 offset1:74
	s_waitcnt vmcnt(24)
	ds_write2_b32 v13, v43, v44 offset0:140 offset1:206
	s_waitcnt vmcnt(22)
	ds_write2_b32 v14, v45, v46 offset0:16 offset1:82
	s_waitcnt vmcnt(20)
	ds_write2_b32 v14, v47, v48 offset0:148 offset1:214
	s_waitcnt vmcnt(18)
	ds_write2_b32 v15, v49, v50 offset0:24 offset1:90
	s_waitcnt vmcnt(16)
	ds_write2_b32 v15, v51, v52 offset0:156 offset1:222
	s_waitcnt vmcnt(14)
	ds_write2_b32 v16, v53, v54 offset0:32 offset1:98
	s_waitcnt vmcnt(12)
	ds_write2_b32 v16, v55, v56 offset0:164 offset1:230
	s_waitcnt vmcnt(10)
	ds_write2_b32 v17, v57, v58 offset0:40 offset1:106
	s_waitcnt vmcnt(8)
	ds_write2_b32 v17, v59, v36 offset0:172 offset1:238
	s_waitcnt vmcnt(6)
	ds_write2_b32 v18, v22, v23 offset0:48 offset1:114
	s_waitcnt vmcnt(4)
	ds_write2_b32 v18, v24, v25 offset0:180 offset1:246
	s_waitcnt vmcnt(2)
	ds_write2_b32 v19, v26, v27 offset0:56 offset1:122
	s_waitcnt vmcnt(0)
	ds_write2_b32 v19, v28, v20 offset0:188 offset1:254
	s_waitcnt lgkmcnt(0)
	ds_read2_b32 v[24:25], v9 offset1:8
	ds_read2_b32 v[28:29], v9 offset0:33 offset1:41
	ds_read2_b32 v[30:31], v9 offset0:66 offset1:74
	s_addc_u32 s93, s36, 0
	v_mov_b32_e32 v5, v3
	ds_read2_b32 v[32:33], v9 offset0:99 offset1:107
	v_lshl_add_u64 v[20:21], s[92:93], 0, v[4:5]
	s_mov_b64 s[36:37], 0x900000
	s_waitcnt lgkmcnt(3)
	v_bfe_u32 v5, v24, 16, 1
	v_lshl_add_u64 v[26:27], v[20:21], 0, s[36:37]
	v_add3_u32 v5, v24, v5, s51
	s_waitcnt lgkmcnt(2)
	v_bfe_u32 v20, v28, 16, 1
	ds_read2_b32 v[34:35], v9 offset0:132 offset1:140
	v_lshrrev_b32_e32 v5, 16, v5
	v_add3_u32 v20, v28, v20, s51
	ds_read2_b32 v[36:37], v9 offset0:165 offset1:173
	v_and_or_b32 v20, v20, s52, v5
	s_waitcnt lgkmcnt(3)
	v_bfe_u32 v5, v30, 16, 1
	v_add3_u32 v5, v30, v5, s51
	s_waitcnt lgkmcnt(2)
	v_bfe_u32 v21, v32, 16, 1
	ds_read2_b32 v[38:39], v9 offset0:198 offset1:206
	v_lshrrev_b32_e32 v5, 16, v5
	v_add3_u32 v21, v32, v21, s51
	ds_read2_b32 v[40:41], v9 offset0:231 offset1:239
	v_and_or_b32 v21, v21, s52, v5
	s_waitcnt lgkmcnt(3)
	v_bfe_u32 v5, v34, 16, 1
	v_add3_u32 v5, v34, v5, s51
	s_waitcnt lgkmcnt(2)
	v_bfe_u32 v22, v36, 16, 1
	v_lshrrev_b32_e32 v5, 16, v5
	v_add3_u32 v22, v36, v22, s51
	v_and_or_b32 v22, v22, s52, v5
	s_waitcnt lgkmcnt(1)
	v_bfe_u32 v5, v38, 16, 1
	v_add3_u32 v5, v38, v5, s51
	s_waitcnt lgkmcnt(0)
	v_bfe_u32 v23, v40, 16, 1
	v_lshrrev_b32_e32 v5, 16, v5
	v_add3_u32 v23, v40, v23, s51
	v_and_or_b32 v23, v23, s52, v5
	v_or_b32_e32 v5, s30, v8
	v_lshlrev_b32_e32 v42, 11, v5
	v_mov_b32_e32 v43, v3
	v_lshl_add_u64 v[42:43], v[26:27], 0, v[42:43]
	v_bfe_u32 v5, v25, 16, 1
	global_store_dwordx4 v[42:43], v[20:23], off sc1
	v_add3_u32 v5, v25, v5, s51
	v_lshrrev_b32_e32 v5, 16, v5
	v_bfe_u32 v20, v29, 16, 1
	v_add3_u32 v20, v29, v20, s51
	v_and_or_b32 v20, v20, s52, v5
	v_bfe_u32 v5, v31, 16, 1
	v_add3_u32 v5, v31, v5, s51
	v_bfe_u32 v21, v33, 16, 1
	v_lshrrev_b32_e32 v5, 16, v5
	v_add3_u32 v21, v33, v21, s51
	v_and_or_b32 v21, v21, s52, v5
	v_bfe_u32 v5, v35, 16, 1
	v_add3_u32 v5, v35, v5, s51
	v_bfe_u32 v22, v37, 16, 1
	v_lshrrev_b32_e32 v5, 16, v5
	v_add3_u32 v22, v37, v22, s51
	v_and_or_b32 v22, v22, s52, v5
	v_bfe_u32 v5, v39, 16, 1
	v_add3_u32 v5, v39, v5, s51
	v_bfe_u32 v23, v41, 16, 1
	v_lshrrev_b32_e32 v5, 16, v5
	v_add3_u32 v23, v41, v23, s51
	v_and_or_b32 v23, v23, s52, v5
	v_or_b32_e32 v5, s30, v10
	v_lshlrev_b32_e32 v24, 11, v5
	v_mov_b32_e32 v25, v3
	ds_read2_b32 v[28:29], v9 offset0:16 offset1:24
	v_lshl_add_u64 v[24:25], v[26:27], 0, v[24:25]
	global_store_dwordx4 v[24:25], v[20:23], off sc1
	ds_read2_b32 v[24:25], v9 offset0:49 offset1:57
	ds_read2_b32 v[30:31], v9 offset0:82 offset1:90
	ds_read2_b32 v[32:33], v9 offset0:115 offset1:123
	s_waitcnt lgkmcnt(3)
	v_bfe_u32 v5, v28, 16, 1
	v_add3_u32 v5, v28, v5, s51
	s_waitcnt lgkmcnt(2)
	v_bfe_u32 v20, v24, 16, 1
	ds_read2_b32 v[34:35], v9 offset0:148 offset1:156
	v_lshrrev_b32_e32 v5, 16, v5
	v_add3_u32 v20, v24, v20, s51
	ds_read2_b32 v[36:37], v9 offset0:181 offset1:189
	v_and_or_b32 v20, v20, s52, v5
	s_waitcnt lgkmcnt(3)
	v_bfe_u32 v5, v30, 16, 1
	v_add3_u32 v5, v30, v5, s51
	s_waitcnt lgkmcnt(2)
	v_bfe_u32 v21, v32, 16, 1
	ds_read2_b32 v[38:39], v9 offset0:214 offset1:222
	v_lshrrev_b32_e32 v5, 16, v5
	v_add3_u32 v21, v32, v21, s51
	ds_read2_b32 v[40:41], v9 offset0:247 offset1:255
	v_and_or_b32 v21, v21, s52, v5
	s_waitcnt lgkmcnt(3)
	v_bfe_u32 v5, v34, 16, 1
	v_add3_u32 v5, v34, v5, s51
	s_waitcnt lgkmcnt(2)
	v_bfe_u32 v22, v36, 16, 1
	v_lshrrev_b32_e32 v5, 16, v5
	v_add3_u32 v22, v36, v22, s51
	v_and_or_b32 v22, v22, s52, v5
	s_waitcnt lgkmcnt(1)
	v_bfe_u32 v5, v38, 16, 1
	v_add3_u32 v5, v38, v5, s51
	s_waitcnt lgkmcnt(0)
	v_bfe_u32 v23, v40, 16, 1
	v_lshrrev_b32_e32 v5, 16, v5
	v_add3_u32 v23, v40, v23, s51
	v_and_or_b32 v23, v23, s52, v5
	v_or_b32_e32 v5, s30, v11
	v_lshlrev_b32_e32 v42, 11, v5
	v_mov_b32_e32 v43, v3
	v_lshl_add_u64 v[42:43], v[26:27], 0, v[42:43]
	v_bfe_u32 v5, v29, 16, 1
	global_store_dwordx4 v[42:43], v[20:23], off sc1
	v_add3_u32 v5, v29, v5, s51
	v_lshrrev_b32_e32 v5, 16, v5
	v_bfe_u32 v20, v25, 16, 1
	v_add3_u32 v20, v25, v20, s51
	v_and_or_b32 v20, v20, s52, v5
	v_bfe_u32 v5, v31, 16, 1
	v_add3_u32 v5, v31, v5, s51
	v_bfe_u32 v21, v33, 16, 1
	v_lshrrev_b32_e32 v5, 16, v5
	v_add3_u32 v21, v33, v21, s51
	v_and_or_b32 v21, v21, s52, v5
	v_bfe_u32 v5, v35, 16, 1
	v_add3_u32 v5, v35, v5, s51
	v_bfe_u32 v22, v37, 16, 1
	v_lshrrev_b32_e32 v5, 16, v5
	v_add3_u32 v22, v37, v22, s51
	v_and_or_b32 v22, v22, s52, v5
	v_bfe_u32 v5, v39, 16, 1
	v_add3_u32 v5, v39, v5, s51
	v_bfe_u32 v23, v41, 16, 1
	v_lshrrev_b32_e32 v5, 16, v5
	v_add3_u32 v23, v41, v23, s51
	v_and_or_b32 v23, v23, s52, v5
	v_or_b32_e32 v5, s30, v12
	v_lshlrev_b32_e32 v24, 11, v5
	v_mov_b32_e32 v25, v3
	v_lshl_add_u64 v[24:25], v[26:27], 0, v[24:25]
	global_store_dwordx4 v[24:25], v[20:23], off sc1
	s_waitcnt lgkmcnt(0)

.LBB0_37:
	s_andn2_b64 vcc, exec, s[36:37]
	s_cbranch_vccnz .LBB0_22
	s_mul_i32 s35, s34, 0x1200000
	s_mul_hi_i32 s30, s34, 0x1200000
	s_waitcnt lgkmcnt(0)
	s_add_u32 s37, s24, s35
	s_addc_u32 s93, s25, s30
	s_mul_hi_i32 s30, s34, 0xf00000
	s_mul_i32 s34, s34, 0xf00000
	s_add_u32 s92, s20, s34
	s_mul_i32 s34, s91, 0xe39
	s_addc_u32 s30, s21, s30
	s_lshr_b32 s35, s34, 31
	s_ashr_i32 s34, s34, 19
	s_add_i32 s34, s34, s35
	s_sext_i32_i16 s35, s34
	s_mulk_i32 s34, 0x90
	s_sub_i32 s34, s91, s34
	s_sext_i32_i16 s34, s34
	s_lshl_b32 s34, s34, 5
	s_lshl_b32 s36, s35, 6
	s_ashr_i32 s35, s34, 31
	s_lshl_b64 s[94:95], s[34:35], 2
	v_or_b32_e32 v5, s36, v6
	s_add_u32 s94, s37, s94
	s_addc_u32 s95, s93, s95
	v_mul_i32_i24_e32 v22, 0x1200, v5
	v_lshl_add_u64 v[20:21], s[94:95], 0, v[2:3]
	v_ashrrev_i32_e32 v23, 31, v22
	v_lshl_add_u64 v[20:21], v[22:23], 2, v[20:21]
	s_mov_b32 s35, 0x9000
	v_add_co_u32_e32 v22, vcc, s35, v20
	s_mov_b32 s35, 0x1b000
	s_nop 0
	v_addc_co_u32_e32 v23, vcc, 0, v21, vcc
	v_add_co_u32_e32 v24, vcc, s60, v20
	s_ashr_i32 s37, s36, 31
	s_nop 0
	v_addc_co_u32_e32 v25, vcc, 0, v21, vcc
	v_add_co_u32_e32 v26, vcc, s35, v20
	s_mov_b32 s35, 0x2d000
	s_nop 0
	v_addc_co_u32_e32 v27, vcc, 0, v21, vcc
	v_add_co_u32_e32 v28, vcc, s69, v20
	s_lshl_b64 s[36:37], s[36:37], 1
	s_nop 0
	v_addc_co_u32_e32 v29, vcc, 0, v21, vcc
	v_add_co_u32_e32 v30, vcc, s35, v20
	s_mov_b32 s35, 0x3f000
	s_nop 0
	v_addc_co_u32_e32 v31, vcc, 0, v21, vcc
	v_add_co_u32_e32 v32, vcc, s78, v20
	s_add_u32 s36, s92, s36
	s_nop 0
	v_addc_co_u32_e32 v33, vcc, 0, v21, vcc
	v_add_co_u32_e32 v34, vcc, s35, v20
	s_mov_b32 s35, 0x51000
	s_nop 0
	v_addc_co_u32_e32 v35, vcc, 0, v21, vcc
	global_load_dword v5, v[20:21], off nt
	global_load_dword v38, v[22:23], off nt
	global_load_dword v39, v[24:25], off nt
	global_load_dword v40, v[26:27], off nt
	global_load_dword v41, v[28:29], off nt
	global_load_dword v42, v[30:31], off nt
	global_load_dword v43, v[32:33], off nt
	global_load_dword v44, v[34:35], off nt
	v_add_co_u32_e32 v22, vcc, s83, v20
	s_addc_u32 s37, s30, s37
	s_nop 0
	v_addc_co_u32_e32 v23, vcc, 0, v21, vcc
	v_add_co_u32_e32 v24, vcc, s35, v20
	s_mov_b32 s35, 0x63000
	s_nop 0
	v_addc_co_u32_e32 v25, vcc, 0, v21, vcc
	v_add_co_u32_e32 v26, vcc, s84, v20
	s_nop 1
	v_addc_co_u32_e32 v27, vcc, 0, v21, vcc
	v_add_co_u32_e32 v28, vcc, s35, v20
	s_mov_b32 s35, 0x75000
	s_nop 0
	v_addc_co_u32_e32 v29, vcc, 0, v21, vcc
	v_add_co_u32_e32 v30, vcc, s85, v20
	s_nop 1
	v_addc_co_u32_e32 v31, vcc, 0, v21, vcc
	v_add_co_u32_e32 v32, vcc, s35, v20
	s_mov_b32 s35, 0x87000
	s_nop 0
	v_addc_co_u32_e32 v33, vcc, 0, v21, vcc
	v_add_co_u32_e32 v34, vcc, s86, v20
	s_nop 1
	v_addc_co_u32_e32 v35, vcc, 0, v21, vcc
	v_add_co_u32_e32 v36, vcc, s35, v20
	s_mov_b32 s35, 0x99000
	s_nop 0
	v_addc_co_u32_e32 v37, vcc, 0, v21, vcc
	global_load_dword v45, v[22:23], off nt
	global_load_dword v46, v[24:25], off nt
	global_load_dword v47, v[26:27], off nt
	global_load_dword v48, v[28:29], off nt
	global_load_dword v49, v[30:31], off nt
	global_load_dword v50, v[32:33], off nt
	global_load_dword v51, v[34:35], off nt
	global_load_dword v52, v[36:37], off nt
	v_add_co_u32_e32 v22, vcc, s87, v20
	s_nop 1
	v_addc_co_u32_e32 v23, vcc, 0, v21, vcc
	v_add_co_u32_e32 v24, vcc, s35, v20
	s_mov_b32 s35, 0xab000
	s_nop 0
	v_addc_co_u32_e32 v25, vcc, 0, v21, vcc
	v_add_co_u32_e32 v26, vcc, s88, v20
	s_nop 1
	v_addc_co_u32_e32 v27, vcc, 0, v21, vcc
	v_add_co_u32_e32 v28, vcc, s35, v20
	s_mov_b32 s35, 0xbd000
	s_nop 0
	v_addc_co_u32_e32 v29, vcc, 0, v21, vcc
	v_add_co_u32_e32 v30, vcc, s89, v20
	s_nop 1
	v_addc_co_u32_e32 v31, vcc, 0, v21, vcc
	v_add_co_u32_e32 v32, vcc, s35, v20
	s_mov_b32 s35, 0xc6000
	s_nop 0
	v_addc_co_u32_e32 v33, vcc, 0, v21, vcc
	v_add_co_u32_e32 v34, vcc, s35, v20
	s_mov_b32 s35, 0xcf000
	s_nop 0
	v_addc_co_u32_e32 v35, vcc, 0, v21, vcc
	v_add_co_u32_e32 v36, vcc, s35, v20
	s_mov_b32 s35, 0xd8000
	s_nop 0
	v_addc_co_u32_e32 v37, vcc, 0, v21, vcc
	global_load_dword v53, v[22:23], off nt
	global_load_dword v54, v[24:25], off nt
	global_load_dword v55, v[26:27], off nt
	global_load_dword v56, v[28:29], off nt
	global_load_dword v57, v[30:31], off nt
	global_load_dword v58, v[32:33], off nt
	global_load_dword v59, v[34:35], off nt
	s_nop 0
	global_load_dword v36, v[36:37], off nt
	v_add_co_u32_e32 v22, vcc, s35, v20
	s_mov_b32 s35, 0xe1000
	s_nop 0
	v_addc_co_u32_e32 v23, vcc, 0, v21, vcc
	v_add_co_u32_e32 v24, vcc, s35, v20
	s_mov_b32 s35, 0xea000
	s_nop 0
	v_addc_co_u32_e32 v25, vcc, 0, v21, vcc
	v_add_co_u32_e32 v26, vcc, s35, v20
	s_mov_b32 s35, 0xf3000
	s_nop 0
	v_addc_co_u32_e32 v27, vcc, 0, v21, vcc
	v_add_co_u32_e32 v28, vcc, s35, v20
	s_mov_b32 s35, 0xfc000
	s_nop 0
	v_addc_co_u32_e32 v29, vcc, 0, v21, vcc
	v_add_co_u32_e32 v30, vcc, s35, v20
	s_mov_b32 s35, 0x105000
	s_nop 0
	v_addc_co_u32_e32 v31, vcc, 0, v21, vcc
	v_add_co_u32_e32 v32, vcc, s35, v20
	s_mov_b32 s35, 0x10e000
	s_nop 0
	v_addc_co_u32_e32 v33, vcc, 0, v21, vcc
	v_add_co_u32_e32 v34, vcc, s35, v20
	s_mov_b32 s35, 0x117000
	s_nop 0
	v_addc_co_u32_e32 v35, vcc, 0, v21, vcc
	v_add_co_u32_e32 v20, vcc, s35, v20
	s_nop 1
	v_addc_co_u32_e32 v21, vcc, 0, v21, vcc
	global_load_dword v22, v[22:23], off nt
	s_nop 0
	global_load_dword v23, v[24:25], off nt
	s_nop 0
	global_load_dword v24, v[26:27], off nt
	global_load_dword v25, v[28:29], off nt
	s_nop 0
	global_load_dword v26, v[30:31], off nt
	global_load_dword v27, v[32:33], off nt
	global_load_dword v28, v[34:35], off nt
	s_nop 0
	global_load_dword v20, v[20:21], off nt
	s_waitcnt vmcnt(30)
	ds_write2_b32 v7, v5, v38 offset1:66
	s_waitcnt vmcnt(28)
	ds_write2_b32 v7, v39, v40 offset0:132 offset1:198
	s_waitcnt vmcnt(26)
	ds_write2_b32 v13, v41, v42 offset0:8 offset1:74
	s_waitcnt vmcnt(24)
	ds_write2_b32 v13, v43, v44 offset0:140 offset1:206
	s_waitcnt vmcnt(22)
	ds_write2_b32 v14, v45, v46 offset0:16 offset1:82
	s_waitcnt vmcnt(20)
	ds_write2_b32 v14, v47, v48 offset0:148 offset1:214
	s_waitcnt vmcnt(18)
	ds_write2_b32 v15, v49, v50 offset0:24 offset1:90
	s_waitcnt vmcnt(16)
	ds_write2_b32 v15, v51, v52 offset0:156 offset1:222
	s_waitcnt vmcnt(14)
	ds_write2_b32 v16, v53, v54 offset0:32 offset1:98
	s_waitcnt vmcnt(12)
	ds_write2_b32 v16, v55, v56 offset0:164 offset1:230
	s_waitcnt vmcnt(10)
	ds_write2_b32 v17, v57, v58 offset0:40 offset1:106
	s_waitcnt vmcnt(8)
	ds_write2_b32 v17, v59, v36 offset0:172 offset1:238
	s_waitcnt vmcnt(6)
	ds_write2_b32 v18, v22, v23 offset0:48 offset1:114
	s_waitcnt vmcnt(4)
	ds_write2_b32 v18, v24, v25 offset0:180 offset1:246
	s_waitcnt vmcnt(2)
	ds_write2_b32 v19, v26, v27 offset0:56 offset1:122
	s_waitcnt vmcnt(0)
	ds_write2_b32 v19, v28, v20 offset0:188 offset1:254
	s_waitcnt lgkmcnt(0)
	ds_read2_b32 v[24:25], v9 offset1:8
	ds_read2_b32 v[28:29], v9 offset0:33 offset1:41
	ds_read2_b32 v[30:31], v9 offset0:66 offset1:74
	v_mov_b32_e32 v5, v3
	ds_read2_b32 v[32:33], v9 offset0:99 offset1:107
	v_lshl_add_u64 v[26:27], s[36:37], 0, v[4:5]
	s_waitcnt lgkmcnt(3)
	v_bfe_u32 v5, v24, 16, 1
	v_add3_u32 v5, v24, v5, s51
	s_waitcnt lgkmcnt(2)
	v_bfe_u32 v20, v28, 16, 1
	ds_read2_b32 v[34:35], v9 offset0:132 offset1:140
	v_lshrrev_b32_e32 v5, 16, v5
	v_add3_u32 v20, v28, v20, s51
	ds_read2_b32 v[36:37], v9 offset0:165 offset1:173
	v_and_or_b32 v20, v20, s52, v5
	s_waitcnt lgkmcnt(3)
	v_bfe_u32 v5, v30, 16, 1
	v_add3_u32 v5, v30, v5, s51
	s_waitcnt lgkmcnt(2)
	v_bfe_u32 v21, v32, 16, 1
	ds_read2_b32 v[38:39], v9 offset0:198 offset1:206
	v_lshrrev_b32_e32 v5, 16, v5
	v_add3_u32 v21, v32, v21, s51
	ds_read2_b32 v[40:41], v9 offset0:231 offset1:239
	v_and_or_b32 v21, v21, s52, v5
	s_waitcnt lgkmcnt(3)
	v_bfe_u32 v5, v34, 16, 1
	v_add3_u32 v5, v34, v5, s51
	s_waitcnt lgkmcnt(2)
	v_bfe_u32 v22, v36, 16, 1
	v_lshrrev_b32_e32 v5, 16, v5
	v_add3_u32 v22, v36, v22, s51
	v_and_or_b32 v22, v22, s52, v5
	s_waitcnt lgkmcnt(1)
	v_bfe_u32 v5, v38, 16, 1
	v_or_b32_e32 v42, s34, v8
	v_add3_u32 v5, v38, v5, s51
	s_waitcnt lgkmcnt(0)
	v_bfe_u32 v23, v40, 16, 1
	v_ashrrev_i32_e32 v43, 31, v42
	v_lshrrev_b32_e32 v5, 16, v5
	v_add3_u32 v23, v40, v23, s51
	v_lshlrev_b64 v[42:43], 11, v[42:43]
	v_and_or_b32 v23, v23, s52, v5
	v_lshl_add_u64 v[42:43], v[26:27], 0, v[42:43]
	v_bfe_u32 v5, v25, 16, 1
	global_store_dwordx4 v[42:43], v[20:23], off sc1
	v_add3_u32 v5, v25, v5, s51
	v_lshrrev_b32_e32 v5, 16, v5
	v_bfe_u32 v20, v29, 16, 1
	v_add3_u32 v20, v29, v20, s51
	v_and_or_b32 v20, v20, s52, v5
	v_bfe_u32 v5, v31, 16, 1
	v_add3_u32 v5, v31, v5, s51
	v_bfe_u32 v21, v33, 16, 1
	v_lshrrev_b32_e32 v5, 16, v5
	v_add3_u32 v21, v33, v21, s51
	v_and_or_b32 v21, v21, s52, v5
	v_bfe_u32 v5, v35, 16, 1
	v_add3_u32 v5, v35, v5, s51
	v_bfe_u32 v22, v37, 16, 1
	v_lshrrev_b32_e32 v5, 16, v5
	v_add3_u32 v22, v37, v22, s51
	v_and_or_b32 v22, v22, s52, v5
	v_bfe_u32 v5, v39, 16, 1
	v_or_b32_e32 v24, s34, v10
	v_add3_u32 v5, v39, v5, s51
	v_bfe_u32 v23, v41, 16, 1
	v_ashrrev_i32_e32 v25, 31, v24
	v_lshrrev_b32_e32 v5, 16, v5
	v_add3_u32 v23, v41, v23, s51
	v_lshlrev_b64 v[24:25], 11, v[24:25]
	v_and_or_b32 v23, v23, s52, v5
	ds_read2_b32 v[28:29], v9 offset0:16 offset1:24
	v_lshl_add_u64 v[24:25], v[26:27], 0, v[24:25]
	global_store_dwordx4 v[24:25], v[20:23], off sc1
	ds_read2_b32 v[24:25], v9 offset0:49 offset1:57
	ds_read2_b32 v[30:31], v9 offset0:82 offset1:90
	ds_read2_b32 v[32:33], v9 offset0:115 offset1:123
	s_waitcnt lgkmcnt(3)
	v_bfe_u32 v5, v28, 16, 1
	v_add3_u32 v5, v28, v5, s51
	s_waitcnt lgkmcnt(2)
	v_bfe_u32 v20, v24, 16, 1
	ds_read2_b32 v[34:35], v9 offset0:148 offset1:156
	v_lshrrev_b32_e32 v5, 16, v5
	v_add3_u32 v20, v24, v20, s51
	ds_read2_b32 v[36:37], v9 offset0:181 offset1:189
	v_and_or_b32 v20, v20, s52, v5
	s_waitcnt lgkmcnt(3)
	v_bfe_u32 v5, v30, 16, 1
	v_add3_u32 v5, v30, v5, s51
	s_waitcnt lgkmcnt(2)
	v_bfe_u32 v21, v32, 16, 1
	ds_read2_b32 v[38:39], v9 offset0:214 offset1:222
	v_lshrrev_b32_e32 v5, 16, v5
	v_add3_u32 v21, v32, v21, s51
	ds_read2_b32 v[40:41], v9 offset0:247 offset1:255
	v_and_or_b32 v21, v21, s52, v5
	s_waitcnt lgkmcnt(3)
	v_bfe_u32 v5, v34, 16, 1
	v_add3_u32 v5, v34, v5, s51
	s_waitcnt lgkmcnt(2)
	v_bfe_u32 v22, v36, 16, 1
	v_lshrrev_b32_e32 v5, 16, v5
	v_add3_u32 v22, v36, v22, s51
	v_and_or_b32 v22, v22, s52, v5
	s_waitcnt lgkmcnt(1)
	v_bfe_u32 v5, v38, 16, 1
	v_or_b32_e32 v42, s34, v11
	v_add3_u32 v5, v38, v5, s51
	s_waitcnt lgkmcnt(0)
	v_bfe_u32 v23, v40, 16, 1
	v_ashrrev_i32_e32 v43, 31, v42
	v_lshrrev_b32_e32 v5, 16, v5
	v_add3_u32 v23, v40, v23, s51
	v_lshlrev_b64 v[42:43], 11, v[42:43]
	v_and_or_b32 v23, v23, s52, v5
	v_lshl_add_u64 v[42:43], v[26:27], 0, v[42:43]
	v_bfe_u32 v5, v29, 16, 1
	global_store_dwordx4 v[42:43], v[20:23], off sc1
	v_add3_u32 v5, v29, v5, s51
	v_lshrrev_b32_e32 v5, 16, v5
	v_bfe_u32 v20, v25, 16, 1
	v_add3_u32 v20, v25, v20, s51
	v_and_or_b32 v20, v20, s52, v5
	v_bfe_u32 v5, v31, 16, 1
	v_add3_u32 v5, v31, v5, s51
	v_bfe_u32 v21, v33, 16, 1
	v_lshrrev_b32_e32 v5, 16, v5
	v_add3_u32 v21, v33, v21, s51
	v_and_or_b32 v21, v21, s52, v5
	v_bfe_u32 v5, v35, 16, 1
	v_add3_u32 v5, v35, v5, s51
	v_bfe_u32 v22, v37, 16, 1
	v_lshrrev_b32_e32 v5, 16, v5
	v_add3_u32 v22, v37, v22, s51
	v_and_or_b32 v22, v22, s52, v5
	v_bfe_u32 v5, v39, 16, 1
	v_or_b32_e32 v24, s34, v12
	v_add3_u32 v5, v39, v5, s51
	v_bfe_u32 v23, v41, 16, 1
	v_ashrrev_i32_e32 v25, 31, v24
	v_lshrrev_b32_e32 v5, 16, v5
	v_add3_u32 v23, v41, v23, s51
	v_lshlrev_b64 v[24:25], 11, v[24:25]
	v_and_or_b32 v23, v23, s52, v5
	v_lshl_add_u64 v[24:25], v[26:27], 0, v[24:25]
	global_store_dwordx4 v[24:25], v[20:23], off sc1
	s_waitcnt lgkmcnt(0)
	s_branch .LBB0_22
